# merge pass: nt (non-temporal) hint on the loop's 32 read-once input loads
# speedup vs baseline: 1.0023x; 1.0023x over previous
.LBB0_495:
	s_nop 0
	v_lshl_add_u64 v[8:9], s[34:35], 0, v[130:131]
	v_add_co_u32_e32 v8, vcc, s11, v8
	s_addk_i32 s10, 0x2000
	s_nop 0
	v_addc_co_u32_e32 v9, vcc, 0, v9, vcc
	global_load_dwordx4 v[84:87], v[8:9], off nt
	global_load_dwordx4 v[80:83], v[8:9], off offset:256 nt
	v_lshl_add_u64 v[8:9], s[34:35], 0, v[128:129]
	v_add_co_u32_e32 v10, vcc, s12, v8
	v_lshl_add_u64 v[128:129], v[128:129], 0, s[6:7]
	s_nop 0
	v_addc_co_u32_e32 v11, vcc, 0, v9, vcc
	global_load_dword v151, v[10:11], off nt
	v_add_co_u32_e32 v10, vcc, s13, v8
	v_lshl_add_u64 v[130:131], v[130:131], 0, s[8:9]
	s_nop 0
	v_addc_co_u32_e32 v11, vcc, 0, v9, vcc
	v_add_co_u32_e32 v8, vcc, s16, v8
	global_load_dword v152, v[10:11], off nt
	s_nop 0
	v_addc_co_u32_e32 v9, vcc, 0, v9, vcc
	global_load_dword v153, v[8:9], off nt
	v_lshl_add_u64 v[8:9], s[34:35], 0, v[126:127]
	v_add_co_u32_e32 v10, vcc, s17, v8
	v_lshl_add_u64 v[126:127], v[126:127], 0, s[4:5]
	s_nop 0
	v_addc_co_u32_e32 v11, vcc, 0, v9, vcc
	global_load_dwordx4 v[72:75], v[10:11], off nt
	v_add_co_u32_e32 v10, vcc, s18, v8
	s_cmpk_lt_i32 s10, 0x2000
	s_nop 0
	v_addc_co_u32_e32 v11, vcc, 0, v9, vcc
	v_add_co_u32_e32 v8, vcc, s19, v8
	global_load_dwordx4 v[76:79], v[10:11], off nt
	s_nop 0
	v_addc_co_u32_e32 v9, vcc, 0, v9, vcc
	global_load_dwordx4 v[68:71], v[8:9], off nt
	v_lshl_add_u64 v[8:9], s[34:35], 0, v[116:117]
	v_add_co_u32_e32 v8, vcc, s11, v8
	v_lshl_add_u64 v[116:117], v[116:117], 0, s[8:9]
	s_nop 0
	v_addc_co_u32_e32 v9, vcc, 0, v9, vcc
	global_load_dwordx4 v[64:67], v[8:9], off nt
	global_load_dwordx4 v[60:63], v[8:9], off offset:256 nt
	v_lshl_add_u64 v[8:9], s[34:35], 0, v[114:115]
	v_add_co_u32_e32 v10, vcc, s12, v8
	v_lshl_add_u64 v[114:115], v[114:115], 0, s[6:7]
	s_nop 0
	v_addc_co_u32_e32 v11, vcc, 0, v9, vcc
	global_load_dword v148, v[10:11], off nt
	v_add_co_u32_e32 v10, vcc, s13, v8
	s_waitcnt vmcnt(10)
	v_lshlrev_b32_e32 v155, 16, v85
	v_addc_co_u32_e32 v11, vcc, 0, v9, vcc
	v_add_co_u32_e32 v8, vcc, s16, v8
	global_load_dword v149, v[10:11], off nt
	s_nop 0
	v_addc_co_u32_e32 v9, vcc, 0, v9, vcc
	global_load_dword v150, v[8:9], off nt
	v_lshl_add_u64 v[8:9], s[34:35], 0, v[112:113]
	v_add_co_u32_e32 v10, vcc, s17, v8
	v_lshlrev_b32_e32 v154, 16, v84
	s_nop 0
	v_addc_co_u32_e32 v11, vcc, 0, v9, vcc
	global_load_dwordx4 v[52:55], v[10:11], off nt
	v_add_co_u32_e32 v10, vcc, s18, v8
	s_waitcnt vmcnt(12)
	v_lshlrev_b32_e32 v157, 16, v81
	v_addc_co_u32_e32 v11, vcc, 0, v9, vcc
	v_add_co_u32_e32 v8, vcc, s19, v8
	v_lshlrev_b32_e32 v156, 16, v80
	s_nop 0
	v_addc_co_u32_e32 v9, vcc, 0, v9, vcc
	v_and_b32_e32 v85, 0xffff0000, v85
	v_and_b32_e32 v84, 0xffff0000, v84
	v_and_b32_e32 v81, 0xffff0000, v81
	v_and_b32_e32 v80, 0xffff0000, v80
	global_load_dwordx4 v[56:59], v[10:11], off nt
	global_load_dwordx4 v[48:51], v[8:9], off nt
	v_lshl_add_u64 v[8:9], s[34:35], 0, v[106:107]
	v_pk_fma_f32 v[154:155], v[122:123], v[156:157], v[154:155] neg_lo:[1,0,0] neg_hi:[1,0,0]
	v_pk_fma_f32 v[80:81], v[122:123], v[80:81], v[84:85] neg_lo:[1,0,0] neg_hi:[1,0,0]
	v_add_co_u32_e32 v8, vcc, s11, v8
	v_pk_mul_f32 v[84:85], v[154:155], v[154:155]
	v_pk_mul_f32 v[156:157], v[80:81], v[80:81]
	v_lshlrev_b32_e32 v159, 16, v87
	v_lshlrev_b32_e32 v158, 16, v86
	v_lshlrev_b32_e32 v161, 16, v83
	v_lshlrev_b32_e32 v160, 16, v82
	v_and_b32_e32 v87, 0xffff0000, v87
	v_and_b32_e32 v86, 0xffff0000, v86
	v_and_b32_e32 v83, 0xffff0000, v83
	v_and_b32_e32 v82, 0xffff0000, v82
	v_addc_co_u32_e32 v9, vcc, 0, v9, vcc
	v_pk_fma_f32 v[158:159], v[122:123], v[160:161], v[158:159] neg_lo:[1,0,0] neg_hi:[1,0,0]
	v_pk_fma_f32 v[82:83], v[122:123], v[82:83], v[86:87] neg_lo:[1,0,0] neg_hi:[1,0,0]
	v_add_f32_e32 v84, v84, v156
	global_load_dwordx4 v[44:47], v[8:9], off nt
	global_load_dwordx4 v[40:43], v[8:9], off offset:256 nt
	v_lshl_add_u64 v[8:9], s[34:35], 0, v[104:105]
	v_mov_b32_e32 v86, v82
	v_mov_b32_e32 v87, v158
	v_add_f32_e32 v84, v85, v84
	v_add_co_u32_e32 v10, vcc, s12, v8
	v_pk_mul_f32 v[86:87], v[86:87], v[86:87]
	v_add_f32_e32 v84, v157, v84
	v_addc_co_u32_e32 v11, vcc, 0, v9, vcc
	v_mov_b32_e32 v160, v83
	v_mov_b32_e32 v161, v159
	v_add_f32_e32 v84, v87, v84
	global_load_dword v145, v[10:11], off nt
	v_add_co_u32_e32 v10, vcc, s13, v8
	v_pk_mul_f32 v[160:161], v[160:161], v[160:161]
	v_add_f32_e32 v84, v86, v84
	v_addc_co_u32_e32 v11, vcc, 0, v9, vcc
	v_add_f32_e32 v84, v161, v84
	v_add_co_u32_e32 v8, vcc, s16, v8
	v_add_f32_e32 v84, v160, v84
	s_nop 0
	v_addc_co_u32_e32 v9, vcc, 0, v9, vcc
	ds_bpermute_b32 v85, v136, v84
	global_load_dword v146, v[10:11], off nt
	global_load_dword v147, v[8:9], off nt
	v_lshl_add_u64 v[8:9], s[34:35], 0, v[102:103]
	v_add_co_u32_e32 v10, vcc, s17, v8
	s_waitcnt lgkmcnt(0)
	v_add_f32_e32 v84, v84, v85
	v_addc_co_u32_e32 v11, vcc, 0, v9, vcc
	global_load_dwordx4 v[32:35], v[10:11], off nt
	v_add_co_u32_e32 v10, vcc, s18, v8
	ds_bpermute_b32 v85, v137, v84
	s_nop 0
	v_addc_co_u32_e32 v11, vcc, 0, v9, vcc
	v_add_co_u32_e32 v8, vcc, s19, v8
	global_load_dwordx4 v[36:39], v[10:11], off nt
	s_nop 0
	v_addc_co_u32_e32 v9, vcc, 0, v9, vcc
	global_load_dwordx4 v[28:31], v[8:9], off nt
	v_lshl_add_u64 v[8:9], s[34:35], 0, v[94:95]
	v_add_co_u32_e32 v8, vcc, s11, v8
	s_waitcnt lgkmcnt(0)
	v_add_f32_e32 v84, v84, v85
	v_addc_co_u32_e32 v9, vcc, 0, v9, vcc
	global_load_dwordx4 v[24:27], v[8:9], off nt
	global_load_dwordx4 v[20:23], v[8:9], off offset:256 nt
	v_lshl_add_u64 v[8:9], s[34:35], 0, v[92:93]
	v_add_co_u32_e32 v10, vcc, s12, v8
	ds_bpermute_b32 v85, v138, v84
	s_nop 0
	v_addc_co_u32_e32 v11, vcc, 0, v9, vcc
	global_load_dword v142, v[10:11], off nt
	v_add_co_u32_e32 v10, vcc, s13, v8
	s_waitcnt lgkmcnt(0)
	v_add_f32_e32 v84, v84, v85
	v_addc_co_u32_e32 v11, vcc, 0, v9, vcc
	v_add_co_u32_e32 v8, vcc, s16, v8
	global_load_dword v143, v[10:11], off nt
	s_nop 0
	v_addc_co_u32_e32 v9, vcc, 0, v9, vcc
	global_load_dword v144, v[8:9], off nt
	v_lshl_add_u64 v[8:9], s[34:35], 0, v[90:91]
	ds_bpermute_b32 v85, v139, v84
	v_add_co_u32_e32 v10, vcc, s17, v8
	v_lshl_add_u64 v[90:91], v[90:91], 0, s[4:5]
	s_nop 0
	v_addc_co_u32_e32 v11, vcc, 0, v9, vcc
	global_load_dwordx4 v[12:15], v[10:11], off nt
	v_add_co_u32_e32 v10, vcc, s18, v8
	s_waitcnt lgkmcnt(0)
	v_add_f32_e32 v84, v84, v85
	v_addc_co_u32_e32 v11, vcc, 0, v9, vcc
	v_add_co_u32_e32 v8, vcc, s19, v8
	v_fmamk_f32 v84, v84, 0x3c000000, v140
	s_nop 0
	v_addc_co_u32_e32 v9, vcc, 0, v9, vcc
	v_cmp_gt_f32_e32 vcc, s21, v84
	v_mul_f32_e32 v85, 0x4f800000, v84
	global_load_dwordx4 v[16:19], v[10:11], off nt
	v_cndmask_b32_e32 v84, v84, v85, vcc
	v_sqrt_f32_e32 v85, v84
	global_load_dwordx4 v[8:11], v[8:9], off nt
	v_lshl_add_u64 v[92:93], v[92:93], 0, s[6:7]
	v_lshl_add_u64 v[94:95], v[94:95], 0, s[8:9]
	v_add_u32_e32 v86, -1, v85
	v_fma_f32 v87, -v86, v85, v84
	v_cmp_ge_f32_e64 s[0:1], 0, v87
	v_add_u32_e32 v87, 1, v85
	v_lshl_add_u64 v[102:103], v[102:103], 0, s[4:5]
	v_cndmask_b32_e64 v86, v85, v86, s[0:1]
	v_fma_f32 v85, -v87, v85, v84
	v_cmp_lt_f32_e64 s[0:1], 0, v85
	v_lshl_add_u64 v[104:105], v[104:105], 0, s[6:7]
	v_lshl_add_u64 v[106:107], v[106:107], 0, s[8:9]
	v_cndmask_b32_e64 v85, v86, v87, s[0:1]
	v_mul_f32_e32 v86, 0x37800000, v85
	v_cndmask_b32_e32 v85, v85, v86, vcc
	v_cmp_class_f32_e32 vcc, v84, v141
	v_lshl_add_u64 v[112:113], v[112:113], 0, s[4:5]
	s_nop 0
	v_cndmask_b32_e32 v84, v85, v84, vcc
	v_div_scale_f32 v85, s[0:1], v84, v84, s22
	v_rcp_f32_e32 v86, v85
	s_nop 0
	v_fma_f32 v87, -v85, v86, 1.0
	v_fmac_f32_e32 v86, v87, v86
	v_div_scale_f32 v87, vcc, s22, v84, s22
	v_mul_f32_e32 v156, v87, v86
	v_fma_f32 v157, -v85, v156, v87
	v_fmac_f32_e32 v156, v157, v86
	v_fma_f32 v85, -v85, v156, v87
	v_div_fmas_f32 v85, v85, v86, v156
	v_div_fixup_f32 v84, v85, v84, s22
	v_pk_mul_f32 v[82:83], v[82:83], v[84:85] op_sel_hi:[1,0]
	v_pk_mul_f32 v[86:87], v[154:155], v[84:85] op_sel_hi:[1,0]
	v_pk_mul_f32 v[82:83], v[4:5], v[82:83]
	v_pk_mul_f32 v[86:87], v[2:3], v[86:87]
	v_pk_mul_f32 v[80:81], v[80:81], v[84:85] op_sel_hi:[1,0]
	v_pk_mul_f32 v[154:155], v[158:159], v[84:85] op_sel_hi:[1,0]
	v_bfe_u32 v84, v83, 16, 1
	v_bfe_u32 v85, v82, 16, 1
	v_pk_mul_f32 v[80:81], v[124:125], v[80:81]
	v_add3_u32 v82, v82, v85, s23
	v_add3_u32 v83, v83, v84, s23
	v_bfe_u32 v84, v86, 16, 1
	v_bfe_u32 v85, v87, 16, 1
	v_pk_mul_f32 v[154:155], v[6:7], v[154:155]
	v_bfe_u32 v156, v81, 16, 1
	v_bfe_u32 v157, v80, 16, 1
	v_add3_u32 v85, v87, v85, s23
	v_add3_u32 v84, v86, v84, s23
	v_add3_u32 v80, v80, v157, s23
	v_add3_u32 v81, v81, v156, s23
	v_bfe_u32 v156, v154, 16, 1
	v_bfe_u32 v157, v155, 16, 1
	v_lshrrev_b32_e32 v84, 16, v84
	v_lshrrev_b32_e32 v85, 16, v85
	v_add3_u32 v155, v155, v157, s23
	v_add3_u32 v154, v154, v156, s23
	v_and_or_b32 v81, v81, s20, v85
	v_and_or_b32 v80, v80, s20, v84
	v_lshl_add_u64 v[84:85], v[100:101], 0, v[134:135]
	v_lshrrev_b32_e32 v86, 16, v154
	v_lshrrev_b32_e32 v87, 16, v155
	v_add_co_u32_e32 v84, vcc, s24, v84
	v_and_or_b32 v83, v83, s20, v87
	v_and_or_b32 v82, v82, s20, v86
	v_addc_co_u32_e32 v85, vcc, -1, v85, vcc
	global_store_dwordx4 v[84:85], v[80:83], off offset:-256 sc1
	v_lshl_add_u64 v[134:135], v[134:135], 0, s[8:9]
	s_waitcnt vmcnt(28)
	v_max3_f32 v80, v151, v152, v153
	v_sub_f32_e32 v81, v151, v80
	v_exp_f32_e32 v83, v81
	v_sub_f32_e32 v81, v152, v80
	v_exp_f32_e32 v82, v81
	v_sub_f32_e32 v80, v153, v80
	v_exp_f32_e32 v80, v80
	v_add_f32_e32 v81, v83, v82
	v_add_f32_e32 v81, v80, v81
	v_div_scale_f32 v84, s[0:1], v81, v81, 1.0
	v_rcp_f32_e32 v85, v84
	s_nop 0
	v_fma_f32 v86, -v84, v85, 1.0
	v_fmac_f32_e32 v85, v86, v85
	v_div_scale_f32 v86, vcc, 1.0, v81, 1.0
	v_mul_f32_e32 v87, v86, v85
	v_fma_f32 v151, -v84, v87, v86
	v_fmac_f32_e32 v87, v151, v85
	v_fma_f32 v84, -v84, v87, v86
	v_div_fmas_f32 v84, v84, v85, v87
	v_div_fixup_f32 v84, v84, v81, 1.0
	v_pk_mul_f32 v[82:83], v[82:83], v[84:85] op_sel_hi:[1,0]
	s_waitcnt vmcnt(26)
	v_lshlrev_b32_e32 v87, 16, v77
	v_lshlrev_b32_e32 v86, 16, v72
	v_mul_f32_e32 v80, v80, v84
	v_lshlrev_b32_e32 v85, 16, v73
	v_lshlrev_b32_e32 v84, 16, v76
	v_pk_mul_f32 v[86:87], v[82:83], v[86:87] op_sel:[1,0] op_sel_hi:[0,1]
	v_pk_fma_f32 v[84:85], v[82:83], v[84:85], v[86:87]
	s_waitcnt vmcnt(25)
	v_lshlrev_b32_e32 v87, 16, v69
	v_lshlrev_b32_e32 v86, 16, v68
	v_pk_fma_f32 v[84:85], v[80:81], v[86:87], v[84:85] op_sel_hi:[0,1,1]
	v_and_b32_e32 v87, 0xffff0000, v73
	v_and_b32_e32 v73, 0xffff0000, v77
	v_and_b32_e32 v72, 0xffff0000, v72
	v_and_b32_e32 v86, 0xffff0000, v76
	v_pk_mul_f32 v[72:73], v[82:83], v[72:73] op_sel:[1,0] op_sel_hi:[0,1]
	v_pk_fma_f32 v[72:73], v[82:83], v[86:87], v[72:73]
	v_and_b32_e32 v69, 0xffff0000, v69
	v_and_b32_e32 v68, 0xffff0000, v68
	v_lshlrev_b32_e32 v77, 16, v79
	v_lshlrev_b32_e32 v76, 16, v74
	v_pk_fma_f32 v[68:69], v[80:81], v[68:69], v[72:73] op_sel_hi:[0,1,1]
	v_lshlrev_b32_e32 v73, 16, v75
	v_lshlrev_b32_e32 v72, 16, v78
	v_pk_mul_f32 v[76:77], v[82:83], v[76:77] op_sel:[1,0] op_sel_hi:[0,1]
	v_pk_fma_f32 v[72:73], v[82:83], v[72:73], v[76:77]
	v_lshlrev_b32_e32 v77, 16, v71
	v_lshlrev_b32_e32 v76, 16, v70
	v_pk_fma_f32 v[72:73], v[80:81], v[76:77], v[72:73] op_sel_hi:[0,1,1]
	v_and_b32_e32 v77, 0xffff0000, v75
	v_and_b32_e32 v75, 0xffff0000, v79
	v_and_b32_e32 v74, 0xffff0000, v74
	v_and_b32_e32 v76, 0xffff0000, v78
	v_pk_mul_f32 v[74:75], v[82:83], v[74:75] op_sel:[1,0] op_sel_hi:[0,1]
	v_pk_fma_f32 v[74:75], v[82:83], v[76:77], v[74:75]
	v_and_b32_e32 v71, 0xffff0000, v71
	v_and_b32_e32 v70, 0xffff0000, v70
	v_bfe_u32 v76, v69, 16, 1
	v_bfe_u32 v77, v68, 16, 1
	v_pk_fma_f32 v[70:71], v[80:81], v[70:71], v[74:75] op_sel_hi:[0,1,1]
	v_add3_u32 v68, v68, v77, s23
	v_add3_u32 v69, v69, v76, s23
	v_bfe_u32 v76, v72, 16, 1
	v_bfe_u32 v77, v73, 16, 1
	v_bfe_u32 v74, v71, 16, 1
	v_bfe_u32 v75, v70, 16, 1
	v_add3_u32 v73, v73, v77, s23
	v_add3_u32 v72, v72, v76, s23
	v_add3_u32 v70, v70, v75, s23
	v_add3_u32 v71, v71, v74, s23
	v_bfe_u32 v74, v84, 16, 1
	v_bfe_u32 v75, v85, 16, 1
	v_lshrrev_b32_e32 v72, 16, v72
	v_lshrrev_b32_e32 v73, 16, v73
	v_add3_u32 v75, v85, v75, s23
	v_add3_u32 v74, v84, v74, s23
	v_and_or_b32 v71, v71, s20, v73
	v_and_or_b32 v70, v70, s20, v72
	v_lshl_add_u64 v[72:73], v[88:89], 0, v[132:133]
	v_lshrrev_b32_e32 v74, 16, v74
	v_lshrrev_b32_e32 v75, 16, v75
	v_add_co_u32_e32 v72, vcc, s25, v72
	v_and_or_b32 v69, v69, s20, v75
	v_and_or_b32 v68, v68, s20, v74
	v_addc_co_u32_e32 v73, vcc, -1, v73, vcc
	global_store_dwordx4 v[72:73], v[68:71], off offset:-3072 sc1
	s_waitcnt vmcnt(25)
	v_lshlrev_b32_e32 v73, 16, v67
	v_lshlrev_b32_e32 v72, 16, v66
	v_lshlrev_b32_e32 v69, 16, v65
	v_lshlrev_b32_e32 v68, 16, v64
	s_waitcnt vmcnt(24)
	v_lshlrev_b32_e32 v71, 16, v61
	v_lshlrev_b32_e32 v70, 16, v60
	v_and_b32_e32 v65, 0xffff0000, v65
	v_and_b32_e32 v64, 0xffff0000, v64
	v_and_b32_e32 v61, 0xffff0000, v61
	v_and_b32_e32 v60, 0xffff0000, v60
	v_pk_fma_f32 v[68:69], v[122:123], v[70:71], v[68:69] neg_lo:[1,0,0] neg_hi:[1,0,0]
	v_pk_fma_f32 v[60:61], v[122:123], v[60:61], v[64:65] neg_lo:[1,0,0] neg_hi:[1,0,0]
	v_pk_mul_f32 v[64:65], v[68:69], v[68:69]
	v_pk_mul_f32 v[70:71], v[60:61], v[60:61]
	v_lshlrev_b32_e32 v75, 16, v63
	v_lshlrev_b32_e32 v74, 16, v62
	v_and_b32_e32 v67, 0xffff0000, v67
	v_and_b32_e32 v66, 0xffff0000, v66
	v_and_b32_e32 v63, 0xffff0000, v63
	v_and_b32_e32 v62, 0xffff0000, v62
	v_pk_fma_f32 v[72:73], v[122:123], v[74:75], v[72:73] neg_lo:[1,0,0] neg_hi:[1,0,0]
	v_pk_fma_f32 v[62:63], v[122:123], v[62:63], v[66:67] neg_lo:[1,0,0] neg_hi:[1,0,0]
	v_add_f32_e32 v64, v64, v70
	v_mov_b32_e32 v66, v62
	v_mov_b32_e32 v67, v72
	v_add_f32_e32 v64, v65, v64
	v_pk_mul_f32 v[66:67], v[66:67], v[66:67]
	v_add_f32_e32 v64, v71, v64
	v_mov_b32_e32 v74, v63
	v_mov_b32_e32 v75, v73
	v_add_f32_e32 v64, v67, v64
	v_pk_mul_f32 v[74:75], v[74:75], v[74:75]
	v_add_f32_e32 v64, v66, v64
	v_add_f32_e32 v64, v75, v64
	v_add_f32_e32 v64, v74, v64
	ds_bpermute_b32 v65, v136, v64
	v_lshl_add_u64 v[132:133], v[132:133], 0, s[8:9]
	s_waitcnt lgkmcnt(0)
	v_add_f32_e32 v64, v64, v65
	ds_bpermute_b32 v65, v137, v64
	s_waitcnt lgkmcnt(0)
	v_add_f32_e32 v64, v64, v65
	ds_bpermute_b32 v65, v138, v64
	s_waitcnt lgkmcnt(0)
	v_add_f32_e32 v64, v64, v65
	ds_bpermute_b32 v65, v139, v64
	s_waitcnt lgkmcnt(0)
	v_add_f32_e32 v64, v64, v65
	v_fmamk_f32 v64, v64, 0x3c000000, v140
	v_cmp_gt_f32_e32 vcc, s21, v64
	v_mul_f32_e32 v65, 0x4f800000, v64
	s_nop 0
	v_cndmask_b32_e32 v64, v64, v65, vcc
	v_sqrt_f32_e32 v65, v64
	s_nop 0
	v_add_u32_e32 v66, -1, v65
	v_fma_f32 v67, -v66, v65, v64
	v_cmp_ge_f32_e64 s[0:1], 0, v67
	v_add_u32_e32 v67, 1, v65
	s_nop 0
	v_cndmask_b32_e64 v66, v65, v66, s[0:1]
	v_fma_f32 v65, -v67, v65, v64
	v_cmp_lt_f32_e64 s[0:1], 0, v65
	s_nop 1
	v_cndmask_b32_e64 v65, v66, v67, s[0:1]
	v_mul_f32_e32 v66, 0x37800000, v65
	v_cndmask_b32_e32 v65, v65, v66, vcc
	v_cmp_class_f32_e32 vcc, v64, v141
	s_nop 1
	v_cndmask_b32_e32 v64, v65, v64, vcc
	v_div_scale_f32 v65, s[0:1], v64, v64, s22
	v_rcp_f32_e32 v66, v65
	s_nop 0
	v_fma_f32 v67, -v65, v66, 1.0
	v_fmac_f32_e32 v66, v67, v66
	v_div_scale_f32 v67, vcc, s22, v64, s22
	v_mul_f32_e32 v70, v67, v66
	v_fma_f32 v71, -v65, v70, v67
	v_fmac_f32_e32 v70, v71, v66
	v_fma_f32 v65, -v65, v70, v67
	v_div_fmas_f32 v65, v65, v66, v70
	v_div_fixup_f32 v64, v65, v64, s22
	v_pk_mul_f32 v[62:63], v[62:63], v[64:65] op_sel_hi:[1,0]
	v_pk_mul_f32 v[66:67], v[68:69], v[64:65] op_sel_hi:[1,0]
	v_pk_mul_f32 v[62:63], v[4:5], v[62:63]
	v_pk_mul_f32 v[66:67], v[2:3], v[66:67]
	v_pk_mul_f32 v[60:61], v[60:61], v[64:65] op_sel_hi:[1,0]
	v_pk_mul_f32 v[68:69], v[72:73], v[64:65] op_sel_hi:[1,0]
	v_bfe_u32 v64, v63, 16, 1
	v_bfe_u32 v65, v62, 16, 1
	v_pk_mul_f32 v[60:61], v[124:125], v[60:61]
	v_add3_u32 v62, v62, v65, s23
	v_add3_u32 v63, v63, v64, s23
	v_bfe_u32 v64, v66, 16, 1
	v_bfe_u32 v65, v67, 16, 1
	v_pk_mul_f32 v[68:69], v[6:7], v[68:69]
	v_bfe_u32 v70, v61, 16, 1
	v_bfe_u32 v71, v60, 16, 1
	v_add3_u32 v65, v67, v65, s23
	v_add3_u32 v64, v66, v64, s23
	v_add3_u32 v60, v60, v71, s23
	v_add3_u32 v61, v61, v70, s23
	v_bfe_u32 v70, v68, 16, 1
	v_bfe_u32 v71, v69, 16, 1
	v_lshrrev_b32_e32 v64, 16, v64
	v_lshrrev_b32_e32 v65, 16, v65
	v_add3_u32 v69, v69, v71, s23
	v_add3_u32 v68, v68, v70, s23
	v_and_or_b32 v61, v61, s20, v65
	v_and_or_b32 v60, v60, s20, v64
	v_lshl_add_u64 v[64:65], v[100:101], 0, v[120:121]
	v_lshrrev_b32_e32 v66, 16, v68
	v_lshrrev_b32_e32 v67, 16, v69
	v_add_co_u32_e32 v64, vcc, s24, v64
	v_and_or_b32 v63, v63, s20, v67
	v_and_or_b32 v62, v62, s20, v66
	v_addc_co_u32_e32 v65, vcc, -1, v65, vcc
	global_store_dwordx4 v[64:65], v[60:63], off offset:-256 sc1
	v_lshl_add_u64 v[120:121], v[120:121], 0, s[8:9]
	s_waitcnt vmcnt(22)
	v_max3_f32 v60, v148, v149, v150
	v_sub_f32_e32 v61, v148, v60
	v_exp_f32_e32 v63, v61
	v_sub_f32_e32 v61, v149, v60
	v_exp_f32_e32 v62, v61
	v_sub_f32_e32 v60, v150, v60
	v_exp_f32_e32 v60, v60
	v_add_f32_e32 v61, v63, v62
	v_add_f32_e32 v61, v60, v61
	v_div_scale_f32 v64, s[0:1], v61, v61, 1.0
	v_rcp_f32_e32 v65, v64
	s_nop 0
	v_fma_f32 v66, -v64, v65, 1.0
	v_fmac_f32_e32 v65, v66, v65
	v_div_scale_f32 v66, vcc, 1.0, v61, 1.0
	v_mul_f32_e32 v67, v66, v65
	v_fma_f32 v68, -v64, v67, v66
	v_fmac_f32_e32 v67, v68, v65
	v_fma_f32 v64, -v64, v67, v66
	v_div_fmas_f32 v64, v64, v65, v67
	v_div_fixup_f32 v64, v64, v61, 1.0
	v_pk_mul_f32 v[62:63], v[62:63], v[64:65] op_sel_hi:[1,0]
	s_waitcnt vmcnt(20)
	v_lshlrev_b32_e32 v67, 16, v57
	v_lshlrev_b32_e32 v66, 16, v52
	v_mul_f32_e32 v60, v60, v64
	v_lshlrev_b32_e32 v65, 16, v53
	v_lshlrev_b32_e32 v64, 16, v56
	v_pk_mul_f32 v[66:67], v[62:63], v[66:67] op_sel:[1,0] op_sel_hi:[0,1]
	v_pk_fma_f32 v[64:65], v[62:63], v[64:65], v[66:67]
	s_waitcnt vmcnt(19)
	v_lshlrev_b32_e32 v67, 16, v49
	v_lshlrev_b32_e32 v66, 16, v48
	v_pk_fma_f32 v[64:65], v[60:61], v[66:67], v[64:65] op_sel_hi:[0,1,1]
	v_and_b32_e32 v67, 0xffff0000, v53
	v_and_b32_e32 v53, 0xffff0000, v57
	v_and_b32_e32 v52, 0xffff0000, v52
	v_and_b32_e32 v66, 0xffff0000, v56
	v_pk_mul_f32 v[52:53], v[62:63], v[52:53] op_sel:[1,0] op_sel_hi:[0,1]
	v_pk_fma_f32 v[52:53], v[62:63], v[66:67], v[52:53]
	v_and_b32_e32 v49, 0xffff0000, v49
	v_and_b32_e32 v48, 0xffff0000, v48
	v_lshlrev_b32_e32 v57, 16, v59
	v_lshlrev_b32_e32 v56, 16, v54
	v_pk_fma_f32 v[48:49], v[60:61], v[48:49], v[52:53] op_sel_hi:[0,1,1]
	v_lshlrev_b32_e32 v53, 16, v55
	v_lshlrev_b32_e32 v52, 16, v58
	v_pk_mul_f32 v[56:57], v[62:63], v[56:57] op_sel:[1,0] op_sel_hi:[0,1]
	v_pk_fma_f32 v[52:53], v[62:63], v[52:53], v[56:57]
	v_lshlrev_b32_e32 v57, 16, v51
	v_lshlrev_b32_e32 v56, 16, v50
	v_pk_fma_f32 v[52:53], v[60:61], v[56:57], v[52:53] op_sel_hi:[0,1,1]
	v_and_b32_e32 v57, 0xffff0000, v55
	v_and_b32_e32 v55, 0xffff0000, v59
	v_and_b32_e32 v54, 0xffff0000, v54
	v_and_b32_e32 v56, 0xffff0000, v58
	v_pk_mul_f32 v[54:55], v[62:63], v[54:55] op_sel:[1,0] op_sel_hi:[0,1]
	v_pk_fma_f32 v[54:55], v[62:63], v[56:57], v[54:55]
	v_and_b32_e32 v51, 0xffff0000, v51
	v_and_b32_e32 v50, 0xffff0000, v50
	v_bfe_u32 v56, v49, 16, 1
	v_bfe_u32 v57, v48, 16, 1
	v_pk_fma_f32 v[50:51], v[60:61], v[50:51], v[54:55] op_sel_hi:[0,1,1]
	v_add3_u32 v48, v48, v57, s23
	v_add3_u32 v49, v49, v56, s23
	v_bfe_u32 v56, v52, 16, 1
	v_bfe_u32 v57, v53, 16, 1
	v_bfe_u32 v54, v51, 16, 1
	v_bfe_u32 v55, v50, 16, 1
	v_add3_u32 v53, v53, v57, s23
	v_add3_u32 v52, v52, v56, s23
	v_add3_u32 v50, v50, v55, s23
	v_add3_u32 v51, v51, v54, s23
	v_bfe_u32 v54, v64, 16, 1
	v_bfe_u32 v55, v65, 16, 1
	v_lshrrev_b32_e32 v52, 16, v52
	v_lshrrev_b32_e32 v53, 16, v53
	v_add3_u32 v55, v65, v55, s23
	v_add3_u32 v54, v64, v54, s23
	v_and_or_b32 v51, v51, s20, v53
	v_and_or_b32 v50, v50, s20, v52
	v_lshl_add_u64 v[52:53], v[88:89], 0, v[118:119]
	v_lshrrev_b32_e32 v54, 16, v54
	v_lshrrev_b32_e32 v55, 16, v55
	v_add_co_u32_e32 v52, vcc, s25, v52
	v_and_or_b32 v49, v49, s20, v55
	v_and_or_b32 v48, v48, s20, v54
	v_addc_co_u32_e32 v53, vcc, -1, v53, vcc
	global_store_dwordx4 v[52:53], v[48:51], off offset:-3072 sc1
	s_waitcnt vmcnt(19)
	v_lshlrev_b32_e32 v53, 16, v47
	v_lshlrev_b32_e32 v52, 16, v46
	v_lshlrev_b32_e32 v49, 16, v45
	v_lshlrev_b32_e32 v48, 16, v44
	s_waitcnt vmcnt(18)
	v_lshlrev_b32_e32 v51, 16, v41
	v_lshlrev_b32_e32 v50, 16, v40
	v_and_b32_e32 v45, 0xffff0000, v45
	v_and_b32_e32 v44, 0xffff0000, v44
	v_and_b32_e32 v41, 0xffff0000, v41
	v_and_b32_e32 v40, 0xffff0000, v40
	v_pk_fma_f32 v[48:49], v[122:123], v[50:51], v[48:49] neg_lo:[1,0,0] neg_hi:[1,0,0]
	v_pk_fma_f32 v[40:41], v[122:123], v[40:41], v[44:45] neg_lo:[1,0,0] neg_hi:[1,0,0]
	v_pk_mul_f32 v[44:45], v[48:49], v[48:49]
	v_pk_mul_f32 v[50:51], v[40:41], v[40:41]
	v_lshlrev_b32_e32 v55, 16, v43
	v_lshlrev_b32_e32 v54, 16, v42
	v_and_b32_e32 v47, 0xffff0000, v47
	v_and_b32_e32 v46, 0xffff0000, v46
	v_and_b32_e32 v43, 0xffff0000, v43
	v_and_b32_e32 v42, 0xffff0000, v42
	v_pk_fma_f32 v[52:53], v[122:123], v[54:55], v[52:53] neg_lo:[1,0,0] neg_hi:[1,0,0]
	v_pk_fma_f32 v[42:43], v[122:123], v[42:43], v[46:47] neg_lo:[1,0,0] neg_hi:[1,0,0]
	v_add_f32_e32 v44, v44, v50
	v_mov_b32_e32 v46, v42
	v_mov_b32_e32 v47, v52
	v_add_f32_e32 v44, v45, v44
	v_pk_mul_f32 v[46:47], v[46:47], v[46:47]
	v_add_f32_e32 v44, v51, v44
	v_mov_b32_e32 v54, v43
	v_mov_b32_e32 v55, v53
	v_add_f32_e32 v44, v47, v44
	v_pk_mul_f32 v[54:55], v[54:55], v[54:55]
	v_add_f32_e32 v44, v46, v44
	v_add_f32_e32 v44, v55, v44
	v_add_f32_e32 v44, v54, v44
	ds_bpermute_b32 v45, v136, v44
	v_lshl_add_u64 v[118:119], v[118:119], 0, s[8:9]
	s_waitcnt lgkmcnt(0)
	v_add_f32_e32 v44, v44, v45
	ds_bpermute_b32 v45, v137, v44
	s_waitcnt lgkmcnt(0)
	v_add_f32_e32 v44, v44, v45
	ds_bpermute_b32 v45, v138, v44
	s_waitcnt lgkmcnt(0)
	v_add_f32_e32 v44, v44, v45
	ds_bpermute_b32 v45, v139, v44
	s_waitcnt lgkmcnt(0)
	v_add_f32_e32 v44, v44, v45
	v_fmamk_f32 v44, v44, 0x3c000000, v140
	v_cmp_gt_f32_e32 vcc, s21, v44
	v_mul_f32_e32 v45, 0x4f800000, v44
	s_nop 0
	v_cndmask_b32_e32 v44, v44, v45, vcc
	v_sqrt_f32_e32 v45, v44
	s_nop 0
	v_add_u32_e32 v46, -1, v45
	v_fma_f32 v47, -v46, v45, v44
	v_cmp_ge_f32_e64 s[0:1], 0, v47
	v_add_u32_e32 v47, 1, v45
	s_nop 0
	v_cndmask_b32_e64 v46, v45, v46, s[0:1]
	v_fma_f32 v45, -v47, v45, v44
	v_cmp_lt_f32_e64 s[0:1], 0, v45
	s_nop 1
	v_cndmask_b32_e64 v45, v46, v47, s[0:1]
	v_mul_f32_e32 v46, 0x37800000, v45
	v_cndmask_b32_e32 v45, v45, v46, vcc
	v_cmp_class_f32_e32 vcc, v44, v141
	s_nop 1
	v_cndmask_b32_e32 v44, v45, v44, vcc
	v_div_scale_f32 v45, s[0:1], v44, v44, s22
	v_rcp_f32_e32 v46, v45
	s_nop 0
	v_fma_f32 v47, -v45, v46, 1.0
	v_fmac_f32_e32 v46, v47, v46
	v_div_scale_f32 v47, vcc, s22, v44, s22
	v_mul_f32_e32 v50, v47, v46
	v_fma_f32 v51, -v45, v50, v47
	v_fmac_f32_e32 v50, v51, v46
	v_fma_f32 v45, -v45, v50, v47
	v_div_fmas_f32 v45, v45, v46, v50
	v_div_fixup_f32 v44, v45, v44, s22
	v_pk_mul_f32 v[42:43], v[42:43], v[44:45] op_sel_hi:[1,0]
	v_pk_mul_f32 v[46:47], v[48:49], v[44:45] op_sel_hi:[1,0]
	v_pk_mul_f32 v[42:43], v[4:5], v[42:43]
	v_pk_mul_f32 v[46:47], v[2:3], v[46:47]
	v_pk_mul_f32 v[40:41], v[40:41], v[44:45] op_sel_hi:[1,0]
	v_pk_mul_f32 v[48:49], v[52:53], v[44:45] op_sel_hi:[1,0]
	v_bfe_u32 v44, v43, 16, 1
	v_bfe_u32 v45, v42, 16, 1
	v_pk_mul_f32 v[40:41], v[124:125], v[40:41]
	v_add3_u32 v42, v42, v45, s23
	v_add3_u32 v43, v43, v44, s23
	v_bfe_u32 v44, v46, 16, 1
	v_bfe_u32 v45, v47, 16, 1
	v_pk_mul_f32 v[48:49], v[6:7], v[48:49]
	v_bfe_u32 v50, v41, 16, 1
	v_bfe_u32 v51, v40, 16, 1
	v_add3_u32 v45, v47, v45, s23
	v_add3_u32 v44, v46, v44, s23
	v_add3_u32 v40, v40, v51, s23
	v_add3_u32 v41, v41, v50, s23
	v_bfe_u32 v50, v48, 16, 1
	v_bfe_u32 v51, v49, 16, 1
	v_lshrrev_b32_e32 v44, 16, v44
	v_lshrrev_b32_e32 v45, 16, v45
	v_add3_u32 v49, v49, v51, s23
	v_add3_u32 v48, v48, v50, s23
	v_and_or_b32 v41, v41, s20, v45
	v_and_or_b32 v40, v40, s20, v44
	v_lshl_add_u64 v[44:45], v[100:101], 0, v[110:111]
	v_lshrrev_b32_e32 v46, 16, v48
	v_lshrrev_b32_e32 v47, 16, v49
	v_add_co_u32_e32 v44, vcc, s24, v44
	v_and_or_b32 v43, v43, s20, v47
	v_and_or_b32 v42, v42, s20, v46
	v_addc_co_u32_e32 v45, vcc, -1, v45, vcc
	global_store_dwordx4 v[44:45], v[40:43], off offset:-256 sc1
	v_lshl_add_u64 v[110:111], v[110:111], 0, s[8:9]
	s_waitcnt vmcnt(16)
	v_max3_f32 v40, v145, v146, v147
	v_sub_f32_e32 v41, v145, v40
	v_exp_f32_e32 v43, v41
	v_sub_f32_e32 v41, v146, v40
	v_exp_f32_e32 v42, v41
	v_sub_f32_e32 v40, v147, v40
	v_exp_f32_e32 v40, v40
	v_add_f32_e32 v41, v43, v42
	v_add_f32_e32 v41, v40, v41
	v_div_scale_f32 v44, s[0:1], v41, v41, 1.0
	v_rcp_f32_e32 v45, v44
	s_nop 0
	v_fma_f32 v46, -v44, v45, 1.0
	v_fmac_f32_e32 v45, v46, v45
	v_div_scale_f32 v46, vcc, 1.0, v41, 1.0
	v_mul_f32_e32 v47, v46, v45
	v_fma_f32 v48, -v44, v47, v46
	v_fmac_f32_e32 v47, v48, v45
	v_fma_f32 v44, -v44, v47, v46
	v_div_fmas_f32 v44, v44, v45, v47
	v_div_fixup_f32 v44, v44, v41, 1.0
	v_pk_mul_f32 v[42:43], v[42:43], v[44:45] op_sel_hi:[1,0]
	s_waitcnt vmcnt(14)
	v_lshlrev_b32_e32 v47, 16, v37
	v_lshlrev_b32_e32 v46, 16, v32
	v_mul_f32_e32 v40, v40, v44
	v_lshlrev_b32_e32 v45, 16, v33
	v_lshlrev_b32_e32 v44, 16, v36
	v_pk_mul_f32 v[46:47], v[42:43], v[46:47] op_sel:[1,0] op_sel_hi:[0,1]
	v_pk_fma_f32 v[44:45], v[42:43], v[44:45], v[46:47]
	s_waitcnt vmcnt(13)
	v_lshlrev_b32_e32 v47, 16, v29
	v_lshlrev_b32_e32 v46, 16, v28
	v_pk_fma_f32 v[44:45], v[40:41], v[46:47], v[44:45] op_sel_hi:[0,1,1]
	v_and_b32_e32 v47, 0xffff0000, v33
	v_and_b32_e32 v33, 0xffff0000, v37
	v_and_b32_e32 v32, 0xffff0000, v32
	v_and_b32_e32 v46, 0xffff0000, v36
	v_pk_mul_f32 v[32:33], v[42:43], v[32:33] op_sel:[1,0] op_sel_hi:[0,1]
	v_pk_fma_f32 v[32:33], v[42:43], v[46:47], v[32:33]
	v_and_b32_e32 v29, 0xffff0000, v29
	v_and_b32_e32 v28, 0xffff0000, v28
	v_lshlrev_b32_e32 v37, 16, v39
	v_lshlrev_b32_e32 v36, 16, v34
	v_pk_fma_f32 v[28:29], v[40:41], v[28:29], v[32:33] op_sel_hi:[0,1,1]
	v_lshlrev_b32_e32 v33, 16, v35
	v_lshlrev_b32_e32 v32, 16, v38
	v_pk_mul_f32 v[36:37], v[42:43], v[36:37] op_sel:[1,0] op_sel_hi:[0,1]
	v_pk_fma_f32 v[32:33], v[42:43], v[32:33], v[36:37]
	v_lshlrev_b32_e32 v37, 16, v31
	v_lshlrev_b32_e32 v36, 16, v30
	v_pk_fma_f32 v[32:33], v[40:41], v[36:37], v[32:33] op_sel_hi:[0,1,1]
	v_and_b32_e32 v37, 0xffff0000, v35
	v_and_b32_e32 v35, 0xffff0000, v39
	v_and_b32_e32 v34, 0xffff0000, v34
	v_and_b32_e32 v36, 0xffff0000, v38
	v_pk_mul_f32 v[34:35], v[42:43], v[34:35] op_sel:[1,0] op_sel_hi:[0,1]
	v_pk_fma_f32 v[34:35], v[42:43], v[36:37], v[34:35]
	v_and_b32_e32 v31, 0xffff0000, v31
	v_and_b32_e32 v30, 0xffff0000, v30
	v_bfe_u32 v36, v29, 16, 1
	v_bfe_u32 v37, v28, 16, 1
	v_pk_fma_f32 v[30:31], v[40:41], v[30:31], v[34:35] op_sel_hi:[0,1,1]
	v_add3_u32 v28, v28, v37, s23
	v_add3_u32 v29, v29, v36, s23
	v_bfe_u32 v36, v32, 16, 1
	v_bfe_u32 v37, v33, 16, 1
	v_bfe_u32 v34, v31, 16, 1
	v_bfe_u32 v35, v30, 16, 1
	v_add3_u32 v33, v33, v37, s23
	v_add3_u32 v32, v32, v36, s23
	v_add3_u32 v30, v30, v35, s23
	v_add3_u32 v31, v31, v34, s23
	v_bfe_u32 v34, v44, 16, 1
	v_bfe_u32 v35, v45, 16, 1
	v_lshrrev_b32_e32 v32, 16, v32
	v_lshrrev_b32_e32 v33, 16, v33
	v_add3_u32 v35, v45, v35, s23
	v_add3_u32 v34, v44, v34, s23
	v_and_or_b32 v31, v31, s20, v33
	v_and_or_b32 v30, v30, s20, v32
	v_lshl_add_u64 v[32:33], v[88:89], 0, v[108:109]
	v_lshrrev_b32_e32 v34, 16, v34
	v_lshrrev_b32_e32 v35, 16, v35
	v_add_co_u32_e32 v32, vcc, s25, v32
	v_and_or_b32 v29, v29, s20, v35
	v_and_or_b32 v28, v28, s20, v34
	v_addc_co_u32_e32 v33, vcc, -1, v33, vcc
	global_store_dwordx4 v[32:33], v[28:31], off offset:-3072 sc1
	s_waitcnt vmcnt(13)
	v_lshlrev_b32_e32 v33, 16, v27
	v_lshlrev_b32_e32 v32, 16, v26
	v_lshlrev_b32_e32 v29, 16, v25
	v_lshlrev_b32_e32 v28, 16, v24
	s_waitcnt vmcnt(12)
	v_lshlrev_b32_e32 v31, 16, v21
	v_lshlrev_b32_e32 v30, 16, v20
	v_and_b32_e32 v25, 0xffff0000, v25
	v_and_b32_e32 v24, 0xffff0000, v24
	v_and_b32_e32 v21, 0xffff0000, v21
	v_and_b32_e32 v20, 0xffff0000, v20
	v_pk_fma_f32 v[28:29], v[122:123], v[30:31], v[28:29] neg_lo:[1,0,0] neg_hi:[1,0,0]
	v_pk_fma_f32 v[20:21], v[122:123], v[20:21], v[24:25] neg_lo:[1,0,0] neg_hi:[1,0,0]
	v_pk_mul_f32 v[24:25], v[28:29], v[28:29]
	v_pk_mul_f32 v[30:31], v[20:21], v[20:21]
	v_lshlrev_b32_e32 v35, 16, v23
	v_lshlrev_b32_e32 v34, 16, v22
	v_and_b32_e32 v27, 0xffff0000, v27
	v_and_b32_e32 v26, 0xffff0000, v26
	v_and_b32_e32 v23, 0xffff0000, v23
	v_and_b32_e32 v22, 0xffff0000, v22
	v_pk_fma_f32 v[32:33], v[122:123], v[34:35], v[32:33] neg_lo:[1,0,0] neg_hi:[1,0,0]
	v_pk_fma_f32 v[22:23], v[122:123], v[22:23], v[26:27] neg_lo:[1,0,0] neg_hi:[1,0,0]
	v_add_f32_e32 v24, v24, v30
	v_mov_b32_e32 v26, v22
	v_mov_b32_e32 v27, v32
	v_add_f32_e32 v24, v25, v24
	v_pk_mul_f32 v[26:27], v[26:27], v[26:27]
	v_add_f32_e32 v24, v31, v24
	v_mov_b32_e32 v34, v23
	v_mov_b32_e32 v35, v33
	v_add_f32_e32 v24, v27, v24
	v_pk_mul_f32 v[34:35], v[34:35], v[34:35]
	v_add_f32_e32 v24, v26, v24
	v_add_f32_e32 v24, v35, v24
	v_add_f32_e32 v24, v34, v24
	ds_bpermute_b32 v25, v136, v24
	v_lshl_add_u64 v[108:109], v[108:109], 0, s[8:9]
	s_waitcnt lgkmcnt(0)
	v_add_f32_e32 v24, v24, v25
	ds_bpermute_b32 v25, v137, v24
	s_waitcnt lgkmcnt(0)
	v_add_f32_e32 v24, v24, v25
	ds_bpermute_b32 v25, v138, v24
	s_waitcnt lgkmcnt(0)
	v_add_f32_e32 v24, v24, v25
	ds_bpermute_b32 v25, v139, v24
	s_waitcnt lgkmcnt(0)
	v_add_f32_e32 v24, v24, v25
	v_fmamk_f32 v24, v24, 0x3c000000, v140
	v_cmp_gt_f32_e32 vcc, s21, v24
	v_mul_f32_e32 v25, 0x4f800000, v24
	s_nop 0
	v_cndmask_b32_e32 v24, v24, v25, vcc
	v_sqrt_f32_e32 v25, v24
	s_nop 0
	v_add_u32_e32 v26, -1, v25
	v_fma_f32 v27, -v26, v25, v24
	v_cmp_ge_f32_e64 s[0:1], 0, v27
	v_add_u32_e32 v27, 1, v25
	s_nop 0
	v_cndmask_b32_e64 v26, v25, v26, s[0:1]
	v_fma_f32 v25, -v27, v25, v24
	v_cmp_lt_f32_e64 s[0:1], 0, v25
	s_nop 1
	v_cndmask_b32_e64 v25, v26, v27, s[0:1]
	v_mul_f32_e32 v26, 0x37800000, v25
	v_cndmask_b32_e32 v25, v25, v26, vcc
	v_cmp_class_f32_e32 vcc, v24, v141
	s_nop 1
	v_cndmask_b32_e32 v24, v25, v24, vcc
	v_div_scale_f32 v25, s[0:1], v24, v24, s22
	v_rcp_f32_e32 v26, v25
	s_nop 0
	v_fma_f32 v27, -v25, v26, 1.0
	v_fmac_f32_e32 v26, v27, v26
	v_div_scale_f32 v27, vcc, s22, v24, s22
	v_mul_f32_e32 v30, v27, v26
	v_fma_f32 v31, -v25, v30, v27
	v_fmac_f32_e32 v30, v31, v26
	v_fma_f32 v25, -v25, v30, v27
	v_div_fmas_f32 v25, v25, v26, v30
	v_div_fixup_f32 v24, v25, v24, s22
	v_pk_mul_f32 v[22:23], v[22:23], v[24:25] op_sel_hi:[1,0]
	v_pk_mul_f32 v[26:27], v[28:29], v[24:25] op_sel_hi:[1,0]
	v_pk_mul_f32 v[22:23], v[4:5], v[22:23]
	v_pk_mul_f32 v[26:27], v[2:3], v[26:27]
	v_pk_mul_f32 v[20:21], v[20:21], v[24:25] op_sel_hi:[1,0]
	v_pk_mul_f32 v[28:29], v[32:33], v[24:25] op_sel_hi:[1,0]
	v_bfe_u32 v24, v23, 16, 1
	v_bfe_u32 v25, v22, 16, 1
	v_pk_mul_f32 v[20:21], v[124:125], v[20:21]
	v_add3_u32 v22, v22, v25, s23
	v_add3_u32 v23, v23, v24, s23
	v_bfe_u32 v24, v26, 16, 1
	v_bfe_u32 v25, v27, 16, 1
	v_pk_mul_f32 v[28:29], v[6:7], v[28:29]
	v_bfe_u32 v30, v21, 16, 1
	v_bfe_u32 v31, v20, 16, 1
	v_add3_u32 v25, v27, v25, s23
	v_add3_u32 v24, v26, v24, s23
	v_add3_u32 v20, v20, v31, s23
	v_add3_u32 v21, v21, v30, s23
	v_bfe_u32 v30, v28, 16, 1
	v_bfe_u32 v31, v29, 16, 1
	v_lshrrev_b32_e32 v24, 16, v24
	v_lshrrev_b32_e32 v25, 16, v25
	v_add3_u32 v29, v29, v31, s23
	v_add3_u32 v28, v28, v30, s23
	v_and_or_b32 v21, v21, s20, v25
	v_and_or_b32 v20, v20, s20, v24
	v_lshl_add_u64 v[24:25], v[100:101], 0, v[98:99]
	v_lshrrev_b32_e32 v26, 16, v28
	v_lshrrev_b32_e32 v27, 16, v29
	v_add_co_u32_e32 v24, vcc, s24, v24
	v_and_or_b32 v23, v23, s20, v27
	v_and_or_b32 v22, v22, s20, v26
	v_addc_co_u32_e32 v25, vcc, -1, v25, vcc
	global_store_dwordx4 v[24:25], v[20:23], off offset:-256 sc1
	v_lshl_add_u64 v[98:99], v[98:99], 0, s[8:9]
	s_waitcnt vmcnt(10)
	v_max3_f32 v20, v142, v143, v144
	v_sub_f32_e32 v21, v142, v20
	v_exp_f32_e32 v23, v21
	v_sub_f32_e32 v21, v143, v20
	v_exp_f32_e32 v22, v21
	v_sub_f32_e32 v20, v144, v20
	v_exp_f32_e32 v20, v20
	v_add_f32_e32 v21, v23, v22
	v_add_f32_e32 v21, v20, v21
	v_div_scale_f32 v24, s[0:1], v21, v21, 1.0
	v_rcp_f32_e32 v25, v24
	s_nop 0
	v_fma_f32 v26, -v24, v25, 1.0
	v_fmac_f32_e32 v25, v26, v25
	v_div_scale_f32 v26, vcc, 1.0, v21, 1.0
	v_mul_f32_e32 v27, v26, v25
	v_fma_f32 v28, -v24, v27, v26
	v_fmac_f32_e32 v27, v28, v25
	v_fma_f32 v24, -v24, v27, v26
	v_div_fmas_f32 v24, v24, v25, v27
	v_div_fixup_f32 v24, v24, v21, 1.0
	v_pk_mul_f32 v[22:23], v[22:23], v[24:25] op_sel_hi:[1,0]
	s_waitcnt vmcnt(8)
	v_lshlrev_b32_e32 v27, 16, v17
	v_lshlrev_b32_e32 v26, 16, v12
	v_mul_f32_e32 v20, v20, v24
	v_lshlrev_b32_e32 v25, 16, v13
	v_lshlrev_b32_e32 v24, 16, v16
	v_pk_mul_f32 v[26:27], v[22:23], v[26:27] op_sel:[1,0] op_sel_hi:[0,1]
	v_pk_fma_f32 v[24:25], v[22:23], v[24:25], v[26:27]
	s_waitcnt vmcnt(7)
	v_lshlrev_b32_e32 v27, 16, v9
	v_lshlrev_b32_e32 v26, 16, v8
	v_pk_fma_f32 v[24:25], v[20:21], v[26:27], v[24:25] op_sel_hi:[0,1,1]
	v_and_b32_e32 v27, 0xffff0000, v13
	v_and_b32_e32 v13, 0xffff0000, v17
	v_and_b32_e32 v12, 0xffff0000, v12
	v_and_b32_e32 v26, 0xffff0000, v16
	v_pk_mul_f32 v[12:13], v[22:23], v[12:13] op_sel:[1,0] op_sel_hi:[0,1]
	v_pk_fma_f32 v[12:13], v[22:23], v[26:27], v[12:13]
	v_and_b32_e32 v9, 0xffff0000, v9
	v_and_b32_e32 v8, 0xffff0000, v8
	v_lshlrev_b32_e32 v17, 16, v19
	v_lshlrev_b32_e32 v16, 16, v14
	v_pk_fma_f32 v[8:9], v[20:21], v[8:9], v[12:13] op_sel_hi:[0,1,1]
	v_lshlrev_b32_e32 v13, 16, v15
	v_lshlrev_b32_e32 v12, 16, v18
	v_pk_mul_f32 v[16:17], v[22:23], v[16:17] op_sel:[1,0] op_sel_hi:[0,1]
	v_pk_fma_f32 v[12:13], v[22:23], v[12:13], v[16:17]
	v_lshlrev_b32_e32 v17, 16, v11
	v_lshlrev_b32_e32 v16, 16, v10
	v_pk_fma_f32 v[12:13], v[20:21], v[16:17], v[12:13] op_sel_hi:[0,1,1]
	v_and_b32_e32 v17, 0xffff0000, v15
	v_and_b32_e32 v15, 0xffff0000, v19
	v_and_b32_e32 v14, 0xffff0000, v14
	v_and_b32_e32 v16, 0xffff0000, v18
	v_pk_mul_f32 v[14:15], v[22:23], v[14:15] op_sel:[1,0] op_sel_hi:[0,1]
	v_pk_fma_f32 v[14:15], v[22:23], v[16:17], v[14:15]
	v_and_b32_e32 v11, 0xffff0000, v11
	v_and_b32_e32 v10, 0xffff0000, v10
	v_bfe_u32 v16, v9, 16, 1
	v_bfe_u32 v17, v8, 16, 1
	v_pk_fma_f32 v[10:11], v[20:21], v[10:11], v[14:15] op_sel_hi:[0,1,1]
	v_add3_u32 v8, v8, v17, s23
	v_add3_u32 v9, v9, v16, s23
	v_bfe_u32 v16, v12, 16, 1
	v_bfe_u32 v17, v13, 16, 1
	v_bfe_u32 v14, v11, 16, 1
	v_bfe_u32 v15, v10, 16, 1
	v_add3_u32 v13, v13, v17, s23
	v_add3_u32 v12, v12, v16, s23
	v_add3_u32 v10, v10, v15, s23
	v_add3_u32 v11, v11, v14, s23
	v_bfe_u32 v14, v24, 16, 1
	v_bfe_u32 v15, v25, 16, 1
	v_lshrrev_b32_e32 v12, 16, v12
	v_lshrrev_b32_e32 v13, 16, v13
	v_add3_u32 v15, v25, v15, s23
	v_add3_u32 v14, v24, v14, s23
	v_and_or_b32 v11, v11, s20, v13
	v_and_or_b32 v10, v10, s20, v12
	v_lshl_add_u64 v[12:13], v[88:89], 0, v[96:97]
	v_lshrrev_b32_e32 v14, 16, v14
	v_lshrrev_b32_e32 v15, 16, v15
	v_add_co_u32_e32 v12, vcc, s25, v12
	v_and_or_b32 v9, v9, s20, v15
	v_and_or_b32 v8, v8, s20, v14
	v_addc_co_u32_e32 v13, vcc, -1, v13, vcc
	v_lshl_add_u64 v[96:97], v[96:97], 0, s[8:9]
	global_store_dwordx4 v[12:13], v[8:11], off offset:-3072 sc1
	s_cbranch_scc1 .LBB0_495
